# cache-policy lever: nt hint on the 8 h stores of the gate/up GEMM epilogue (ph9), best version otherwise
# baseline (speedup 1.0000x reference)
; __device__ __forceinline__ unsigned cvt_pk_bf16(float lo, float hi) { const f32x2_t f = {lo, hi}; const bf16x2_t b = __builtin_convertvector(f, bf16x2_t); return __builtin_bit_cast(unsigned, b); }
;     __device__ __forceinline__ void operator()(const f32x4 (&acc)[2][2][4][2], const Unit& u, int wr, int wc, int fr, int fq) const {
;         const int row0 = u.pm * BM + wr * 64 + fr, col0 = u.pn * HALF + wc * 32 + 8 * fq;
; #pragma unroll
;         for (int ai = 0; ai < 2; ++ai)
; #pragma unroll
;             for (int m = 0; m < 4; ++m) { float o[8];
; #pragma unroll
;                 for (int n = 0; n < 2; ++n)
; #pragma unroll
;                     for (int p = 0; p < 2; ++p) { const f32x2_t gt = {acc[ai][0][m][n][2 * p], acc[ai][0][m][n][2 * p + 1]}, up = {acc[ai][1][m][n][2 * p], acc[ai][1][m][n][2 * p + 1]};
;                         const f32x2_t t = gt * (f32x2_t){-1.44269504f, -1.44269504f}; const f32x2_t e = {__builtin_amdgcn_exp2f(t.x), __builtin_amdgcn_exp2f(t.y)}; const f32x2_t d = e + (f32x2_t){1.f, 1.f};
;                         const f32x2_t r = {__builtin_amdgcn_rcpf(d.x), __builtin_amdgcn_rcpf(d.y)}; const f32x2_t q = (gt * up) * r; o[4 * n + 2 * p] = q.x; o[4 * n + 2 * p + 1] = q.y; }
;                 u32x4 w; w.x = cvt_pk_bf16(o[0], o[1]); w.y = cvt_pk_bf16(o[2], o[3]); w.z = cvt_pk_bf16(o[4], o[5]); w.w = cvt_pk_bf16(o[6], o[7]);
;                 *(u32x4*)(h + (size_t)(row0 + ai * HALF + m * 16) * DFF + col0) = w; }
.LBB0_1243:
	v_pk_mul_f32 v[140:141], v[124:125], s[20:21] op_sel_hi:[1,0]
	v_pk_mul_f32 v[150:151], v[126:127], s[20:21] op_sel_hi:[1,0]
	v_exp_f32_e32 v140, v140
	v_exp_f32_e32 v141, v141
	v_exp_f32_e32 v150, v150
	v_exp_f32_e32 v151, v151
	v_pk_mul_f32 v[152:153], v[94:95], v[126:127]
	v_pk_add_f32 v[140:141], v[140:141], 1.0 op_sel_hi:[1,0]
	v_pk_mul_f32 v[154:155], v[92:93], v[124:125]
	v_pk_add_f32 v[150:151], v[150:151], 1.0 op_sel_hi:[1,0]
	v_rcp_f32_e32 v140, v140
	v_rcp_f32_e32 v141, v141
	v_rcp_f32_e32 v150, v150
	v_rcp_f32_e32 v151, v151
	v_lshl_or_b32 v142, s49, 7, v147
	v_pk_mul_f32 v[140:141], v[154:155], v[140:141]
	v_pk_mul_f32 v[154:155], v[122:123], s[20:21] op_sel_hi:[1,0]
	v_pk_mul_f32 v[152:153], v[152:153], v[150:151]
	v_pk_mul_f32 v[150:151], v[120:121], s[20:21] op_sel_hi:[1,0]
	v_exp_f32_e32 v154, v154
	v_exp_f32_e32 v150, v150
	v_exp_f32_e32 v151, v151
	v_exp_f32_e32 v155, v155
	v_pk_mul_f32 v[156:157], v[90:91], v[122:123]
	v_pk_mul_f32 v[158:159], v[88:89], v[120:121]
	v_pk_add_f32 v[150:151], v[150:151], 1.0 op_sel_hi:[1,0]
	v_pk_add_f32 v[154:155], v[154:155], 1.0 op_sel_hi:[1,0]
	v_rcp_f32_e32 v150, v150
	v_rcp_f32_e32 v151, v151
	v_rcp_f32_e32 v154, v154
	v_rcp_f32_e32 v155, v155
	v_lshl_add_u32 v149, s8, 8, v145
	v_ashrrev_i32_e32 v143, 31, v142
	v_pk_mul_f32 v[158:159], v[158:159], v[150:151]
	v_pk_mul_f32 v[154:155], v[156:157], v[154:155]
	v_cvt_pk_bf16_f32 v150, v140, v141
	v_mov_b64_e32 v[140:141], s[16:17]
	v_cvt_pk_bf16_f32 v151, v152, v153
	v_cvt_pk_bf16_f32 v153, v154, v155
	v_mad_i64_i32 v[154:155], s[30:31], v149, s61, v[140:141]
	v_lshlrev_b64 v[142:143], 1, v[142:143]
	v_cvt_pk_bf16_f32 v152, v158, v159
	v_lshl_add_u64 v[154:155], v[154:155], 0, v[142:143]
	global_store_dwordx4 v[154:155], v[150:153], off nt
	v_pk_mul_f32 v[154:155], v[86:87], v[118:119]
	v_pk_mul_f32 v[156:157], v[84:85], v[116:117]
	v_pk_mul_f32 v[152:153], v[118:119], s[20:21] op_sel_hi:[1,0]
	v_pk_mul_f32 v[150:151], v[116:117], s[20:21] op_sel_hi:[1,0]
	v_exp_f32_e32 v152, v152
	v_exp_f32_e32 v153, v153
	v_exp_f32_e32 v150, v150
	v_exp_f32_e32 v151, v151
	v_pk_mul_f32 v[160:161], v[80:81], v[112:113]
	v_pk_add_f32 v[152:153], v[152:153], 1.0 op_sel_hi:[1,0]
	v_pk_mul_f32 v[158:159], v[82:83], v[114:115]
	v_rcp_f32_e32 v152, v152
	v_rcp_f32_e32 v153, v153
	v_pk_add_f32 v[150:151], v[150:151], 1.0 op_sel_hi:[1,0]
	v_add_u32_e32 v162, 0x80, v149
	v_rcp_f32_e32 v150, v150
	v_rcp_f32_e32 v151, v151
	v_pk_mul_f32 v[152:153], v[154:155], v[152:153]
	v_pk_mul_f32 v[154:155], v[112:113], s[20:21] op_sel_hi:[1,0]
	s_andn2_b64 vcc, exec, s[4:5]
	v_exp_f32_e32 v154, v154
	v_exp_f32_e32 v155, v155
	v_pk_mul_f32 v[150:151], v[156:157], v[150:151]
	v_pk_mul_f32 v[156:157], v[114:115], s[20:21] op_sel_hi:[1,0]
	v_cvt_pk_bf16_f32 v150, v150, v151
	v_exp_f32_e32 v156, v156
	v_exp_f32_e32 v157, v157
	v_pk_add_f32 v[154:155], v[154:155], 1.0 op_sel_hi:[1,0]
	v_cvt_pk_bf16_f32 v151, v152, v153
	v_rcp_f32_e32 v154, v154
	v_rcp_f32_e32 v155, v155
	v_pk_add_f32 v[156:157], v[156:157], 1.0 op_sel_hi:[1,0]
	v_pk_mul_f32 v[154:155], v[160:161], v[154:155]
	v_rcp_f32_e32 v156, v156
	v_rcp_f32_e32 v157, v157
	v_cvt_pk_bf16_f32 v152, v154, v155
	v_or_b32_e32 v154, 16, v149
	v_mad_i64_i32 v[154:155], s[30:31], v154, s61, v[140:141]
	v_pk_mul_f32 v[156:157], v[158:159], v[156:157]
	v_lshl_add_u64 v[154:155], v[154:155], 0, v[142:143]
	v_cvt_pk_bf16_f32 v153, v156, v157
	global_store_dwordx4 v[154:155], v[150:153], off nt
	v_pk_mul_f32 v[154:155], v[78:79], v[110:111]
	v_pk_mul_f32 v[156:157], v[76:77], v[108:109]
	v_pk_mul_f32 v[152:153], v[110:111], s[20:21] op_sel_hi:[1,0]
	v_pk_mul_f32 v[150:151], v[108:109], s[20:21] op_sel_hi:[1,0]
	v_exp_f32_e32 v152, v152
	v_exp_f32_e32 v153, v153
	v_exp_f32_e32 v150, v150
	v_exp_f32_e32 v151, v151
	v_pk_mul_f32 v[160:161], v[72:73], v[104:105]
	v_pk_add_f32 v[152:153], v[152:153], 1.0 op_sel_hi:[1,0]
	v_pk_mul_f32 v[158:159], v[74:75], v[106:107]
	v_rcp_f32_e32 v152, v152
	v_rcp_f32_e32 v153, v153
	v_pk_add_f32 v[150:151], v[150:151], 1.0 op_sel_hi:[1,0]
	v_pk_mul_f32 v[152:153], v[154:155], v[152:153]
	v_rcp_f32_e32 v150, v150
	v_rcp_f32_e32 v151, v151
	v_pk_mul_f32 v[154:155], v[104:105], s[20:21] op_sel_hi:[1,0]
	v_pk_mul_f32 v[150:151], v[156:157], v[150:151]
	v_exp_f32_e32 v154, v154
	v_exp_f32_e32 v155, v155
	v_pk_mul_f32 v[156:157], v[106:107], s[20:21] op_sel_hi:[1,0]
	v_cvt_pk_bf16_f32 v150, v150, v151
	v_exp_f32_e32 v156, v156
	v_exp_f32_e32 v157, v157
	v_pk_add_f32 v[154:155], v[154:155], 1.0 op_sel_hi:[1,0]
	v_cvt_pk_bf16_f32 v151, v152, v153
	v_rcp_f32_e32 v154, v154
	v_rcp_f32_e32 v155, v155
	v_pk_add_f32 v[156:157], v[156:157], 1.0 op_sel_hi:[1,0]
	v_pk_mul_f32 v[154:155], v[160:161], v[154:155]
	v_rcp_f32_e32 v156, v156
	v_rcp_f32_e32 v157, v157
	v_cvt_pk_bf16_f32 v152, v154, v155
	v_or_b32_e32 v154, 32, v149
	v_mad_i64_i32 v[154:155], s[30:31], v154, s61, v[140:141]
	v_pk_mul_f32 v[156:157], v[158:159], v[156:157]
	v_lshl_add_u64 v[154:155], v[154:155], 0, v[142:143]
	v_cvt_pk_bf16_f32 v153, v156, v157
	global_store_dwordx4 v[154:155], v[150:153], off nt
	v_pk_mul_f32 v[154:155], v[70:71], v[102:103]
	v_pk_mul_f32 v[156:157], v[68:69], v[100:101]
	v_pk_mul_f32 v[152:153], v[102:103], s[20:21] op_sel_hi:[1,0]
	v_pk_mul_f32 v[150:151], v[100:101], s[20:21] op_sel_hi:[1,0]
	v_exp_f32_e32 v152, v152
	v_exp_f32_e32 v153, v153
	v_exp_f32_e32 v150, v150
	v_exp_f32_e32 v151, v151
	v_pk_mul_f32 v[160:161], v[64:65], v[96:97]
	v_pk_add_f32 v[152:153], v[152:153], 1.0 op_sel_hi:[1,0]
	v_pk_mul_f32 v[158:159], v[66:67], v[98:99]
	v_rcp_f32_e32 v152, v152
	v_rcp_f32_e32 v153, v153
; __device__ __forceinline__ unsigned cvt_pk_bf16(float lo, float hi) { const f32x2_t f = {lo, hi}; const bf16x2_t b = __builtin_convertvector(f, bf16x2_t); return __builtin_bit_cast(unsigned, b); }
;     __device__ __forceinline__ void operator()(const f32x4 (&acc)[2][2][4][2], const Unit& u, int wr, int wc, int fr, int fq) const {
;     ...
;             for (int m = 0; m < 4; ++m) { float o[8];
; #pragma unroll
;                 for (int n = 0; n < 2; ++n)
; #pragma unroll
;                     for (int p = 0; p < 2; ++p) { const f32x2_t gt = {acc[ai][0][m][n][2 * p], acc[ai][0][m][n][2 * p + 1]}, up = {acc[ai][1][m][n][2 * p], acc[ai][1][m][n][2 * p + 1]};
;                         const f32x2_t t = gt * (f32x2_t){-1.44269504f, -1.44269504f}; const f32x2_t e = {__builtin_amdgcn_exp2f(t.x), __builtin_amdgcn_exp2f(t.y)}; const f32x2_t d = e + (f32x2_t){1.f, 1.f};
;                         const f32x2_t r = {__builtin_amdgcn_rcpf(d.x), __builtin_amdgcn_rcpf(d.y)}; const f32x2_t q = (gt * up) * r; o[4 * n + 2 * p] = q.x; o[4 * n + 2 * p + 1] = q.y; }
;                 u32x4 w; w.x = cvt_pk_bf16(o[0], o[1]); w.y = cvt_pk_bf16(o[2], o[3]); w.z = cvt_pk_bf16(o[4], o[5]); w.w = cvt_pk_bf16(o[6], o[7]);
;                 *(u32x4*)(h + (size_t)(row0 + ai * HALF + m * 16) * DFF + col0) = w; }
	v_pk_add_f32 v[150:151], v[150:151], 1.0 op_sel_hi:[1,0]
	v_pk_mul_f32 v[152:153], v[154:155], v[152:153]
	v_rcp_f32_e32 v150, v150
	v_rcp_f32_e32 v151, v151
	v_pk_mul_f32 v[154:155], v[96:97], s[20:21] op_sel_hi:[1,0]
	v_pk_mul_f32 v[150:151], v[156:157], v[150:151]
	v_exp_f32_e32 v154, v154
	v_exp_f32_e32 v155, v155
	v_pk_mul_f32 v[156:157], v[98:99], s[20:21] op_sel_hi:[1,0]
	v_cvt_pk_bf16_f32 v150, v150, v151
	v_exp_f32_e32 v156, v156
	v_exp_f32_e32 v157, v157
	v_pk_add_f32 v[154:155], v[154:155], 1.0 op_sel_hi:[1,0]
	v_cvt_pk_bf16_f32 v151, v152, v153
	v_rcp_f32_e32 v154, v154
	v_rcp_f32_e32 v155, v155
	v_pk_add_f32 v[156:157], v[156:157], 1.0 op_sel_hi:[1,0]
	v_pk_mul_f32 v[154:155], v[160:161], v[154:155]
	v_rcp_f32_e32 v156, v156
	v_rcp_f32_e32 v157, v157
	v_cvt_pk_bf16_f32 v152, v154, v155
	v_or_b32_e32 v154, 48, v149
	v_mad_i64_i32 v[154:155], s[30:31], v154, s61, v[140:141]
	v_pk_mul_f32 v[156:157], v[158:159], v[156:157]
	v_lshl_add_u64 v[154:155], v[154:155], 0, v[142:143]
	v_cvt_pk_bf16_f32 v153, v156, v157
	global_store_dwordx4 v[154:155], v[150:153], off nt
	v_pk_mul_f32 v[154:155], v[30:31], v[62:63]
	v_pk_mul_f32 v[156:157], v[28:29], v[60:61]
	v_pk_mul_f32 v[152:153], v[62:63], s[20:21] op_sel_hi:[1,0]
	v_pk_mul_f32 v[150:151], v[60:61], s[20:21] op_sel_hi:[1,0]
	v_exp_f32_e32 v152, v152
	v_exp_f32_e32 v153, v153
	v_exp_f32_e32 v150, v150
	v_exp_f32_e32 v151, v151
	v_pk_mul_f32 v[160:161], v[24:25], v[56:57]
	v_pk_add_f32 v[152:153], v[152:153], 1.0 op_sel_hi:[1,0]
	v_pk_mul_f32 v[158:159], v[26:27], v[58:59]
	v_pk_add_f32 v[150:151], v[150:151], 1.0 op_sel_hi:[1,0]
	v_rcp_f32_e32 v152, v152
	v_rcp_f32_e32 v153, v153
	v_rcp_f32_e32 v150, v150
	v_rcp_f32_e32 v151, v151
	v_pk_mul_f32 v[152:153], v[154:155], v[152:153]
	v_pk_mul_f32 v[154:155], v[56:57], s[20:21] op_sel_hi:[1,0]
	v_pk_mul_f32 v[150:151], v[156:157], v[150:151]
	v_exp_f32_e32 v154, v154
	v_exp_f32_e32 v155, v155
	v_pk_mul_f32 v[156:157], v[58:59], s[20:21] op_sel_hi:[1,0]
	v_cvt_pk_bf16_f32 v150, v150, v151
	v_exp_f32_e32 v156, v156
	v_exp_f32_e32 v157, v157
	v_pk_add_f32 v[154:155], v[154:155], 1.0 op_sel_hi:[1,0]
	v_cvt_pk_bf16_f32 v151, v152, v153
	v_rcp_f32_e32 v154, v154
	v_rcp_f32_e32 v155, v155
	v_pk_add_f32 v[156:157], v[156:157], 1.0 op_sel_hi:[1,0]
	v_pk_mul_f32 v[154:155], v[160:161], v[154:155]
	v_rcp_f32_e32 v156, v156
	v_rcp_f32_e32 v157, v157
	v_cvt_pk_bf16_f32 v152, v154, v155
	v_mad_i64_i32 v[154:155], s[30:31], v162, s61, v[140:141]
	v_pk_mul_f32 v[156:157], v[158:159], v[156:157]
	v_lshl_add_u64 v[154:155], v[154:155], 0, v[142:143]
	v_cvt_pk_bf16_f32 v153, v156, v157
	global_store_dwordx4 v[154:155], v[150:153], off nt
	v_pk_mul_f32 v[154:155], v[22:23], v[54:55]
	v_pk_mul_f32 v[156:157], v[20:21], v[52:53]
	v_pk_mul_f32 v[152:153], v[54:55], s[20:21] op_sel_hi:[1,0]
	v_pk_mul_f32 v[150:151], v[52:53], s[20:21] op_sel_hi:[1,0]
	v_exp_f32_e32 v152, v152
	v_exp_f32_e32 v153, v153
	v_exp_f32_e32 v150, v150
	v_exp_f32_e32 v151, v151
	v_pk_mul_f32 v[160:161], v[16:17], v[48:49]
	v_pk_add_f32 v[152:153], v[152:153], 1.0 op_sel_hi:[1,0]
	v_pk_mul_f32 v[158:159], v[18:19], v[50:51]
	v_rcp_f32_e32 v152, v152
	v_rcp_f32_e32 v153, v153
	v_pk_add_f32 v[150:151], v[150:151], 1.0 op_sel_hi:[1,0]
	v_pk_mul_f32 v[152:153], v[154:155], v[152:153]
	v_rcp_f32_e32 v150, v150
	v_rcp_f32_e32 v151, v151
	v_pk_mul_f32 v[154:155], v[48:49], s[20:21] op_sel_hi:[1,0]
	v_pk_mul_f32 v[150:151], v[156:157], v[150:151]
	v_exp_f32_e32 v154, v154
	v_exp_f32_e32 v155, v155
	v_pk_mul_f32 v[156:157], v[50:51], s[20:21] op_sel_hi:[1,0]
	v_cvt_pk_bf16_f32 v150, v150, v151
	v_exp_f32_e32 v156, v156
	v_exp_f32_e32 v157, v157
	v_pk_add_f32 v[154:155], v[154:155], 1.0 op_sel_hi:[1,0]
	v_cvt_pk_bf16_f32 v151, v152, v153
	v_rcp_f32_e32 v154, v154
	v_rcp_f32_e32 v155, v155
; __device__ __forceinline__ unsigned cvt_pk_bf16(float lo, float hi) { const f32x2_t f = {lo, hi}; const bf16x2_t b = __builtin_convertvector(f, bf16x2_t); return __builtin_bit_cast(unsigned, b); }
;     __device__ __forceinline__ void operator()(const f32x4 (&acc)[2][2][4][2], const Unit& u, int wr, int wc, int fr, int fq) const {
;     ...
;             for (int m = 0; m < 4; ++m) { float o[8];
; #pragma unroll
;                 for (int n = 0; n < 2; ++n)
; #pragma unroll
;                     for (int p = 0; p < 2; ++p) { const f32x2_t gt = {acc[ai][0][m][n][2 * p], acc[ai][0][m][n][2 * p + 1]}, up = {acc[ai][1][m][n][2 * p], acc[ai][1][m][n][2 * p + 1]};
;                         const f32x2_t t = gt * (f32x2_t){-1.44269504f, -1.44269504f}; const f32x2_t e = {__builtin_amdgcn_exp2f(t.x), __builtin_amdgcn_exp2f(t.y)}; const f32x2_t d = e + (f32x2_t){1.f, 1.f};
;                         const f32x2_t r = {__builtin_amdgcn_rcpf(d.x), __builtin_amdgcn_rcpf(d.y)}; const f32x2_t q = (gt * up) * r; o[4 * n + 2 * p] = q.x; o[4 * n + 2 * p + 1] = q.y; }
;                 u32x4 w; w.x = cvt_pk_bf16(o[0], o[1]); w.y = cvt_pk_bf16(o[2], o[3]); w.z = cvt_pk_bf16(o[4], o[5]); w.w = cvt_pk_bf16(o[6], o[7]);
;                 *(u32x4*)(h + (size_t)(row0 + ai * HALF + m * 16) * DFF + col0) = w; }
	v_pk_add_f32 v[156:157], v[156:157], 1.0 op_sel_hi:[1,0]
	v_pk_mul_f32 v[154:155], v[160:161], v[154:155]
	v_rcp_f32_e32 v156, v156
	v_rcp_f32_e32 v157, v157
	v_cvt_pk_bf16_f32 v152, v154, v155
	v_add_u32_e32 v154, 0x90, v149
	v_mad_i64_i32 v[154:155], s[30:31], v154, s61, v[140:141]
	v_pk_mul_f32 v[156:157], v[158:159], v[156:157]
	v_lshl_add_u64 v[154:155], v[154:155], 0, v[142:143]
	v_cvt_pk_bf16_f32 v153, v156, v157
	global_store_dwordx4 v[154:155], v[150:153], off nt
	v_pk_mul_f32 v[154:155], v[14:15], v[46:47]
	v_pk_mul_f32 v[156:157], v[12:13], v[44:45]
	v_pk_mul_f32 v[152:153], v[46:47], s[20:21] op_sel_hi:[1,0]
	v_pk_mul_f32 v[150:151], v[44:45], s[20:21] op_sel_hi:[1,0]
	v_exp_f32_e32 v152, v152
	v_exp_f32_e32 v153, v153
	v_exp_f32_e32 v150, v150
	v_exp_f32_e32 v151, v151
	v_pk_mul_f32 v[160:161], v[8:9], v[40:41]
	v_pk_add_f32 v[152:153], v[152:153], 1.0 op_sel_hi:[1,0]
	v_pk_mul_f32 v[158:159], v[10:11], v[42:43]
	v_rcp_f32_e32 v152, v152
	v_rcp_f32_e32 v153, v153
	v_pk_add_f32 v[150:151], v[150:151], 1.0 op_sel_hi:[1,0]
	v_pk_mul_f32 v[152:153], v[154:155], v[152:153]
	v_rcp_f32_e32 v150, v150
	v_rcp_f32_e32 v151, v151
	v_pk_mul_f32 v[154:155], v[40:41], s[20:21] op_sel_hi:[1,0]
	v_pk_mul_f32 v[150:151], v[156:157], v[150:151]
	v_exp_f32_e32 v154, v154
	v_exp_f32_e32 v155, v155
	v_pk_mul_f32 v[156:157], v[42:43], s[20:21] op_sel_hi:[1,0]
	v_cvt_pk_bf16_f32 v150, v150, v151
	v_exp_f32_e32 v156, v156
	v_exp_f32_e32 v157, v157
	v_pk_add_f32 v[154:155], v[154:155], 1.0 op_sel_hi:[1,0]
	v_cvt_pk_bf16_f32 v151, v152, v153
	v_rcp_f32_e32 v154, v154
	v_rcp_f32_e32 v155, v155
	v_pk_add_f32 v[156:157], v[156:157], 1.0 op_sel_hi:[1,0]
	v_pk_mul_f32 v[154:155], v[160:161], v[154:155]
	v_rcp_f32_e32 v156, v156
	v_rcp_f32_e32 v157, v157
	v_cvt_pk_bf16_f32 v152, v154, v155
	v_add_u32_e32 v154, 0xa0, v149
	v_mad_i64_i32 v[154:155], s[30:31], v154, s61, v[140:141]
	v_pk_mul_f32 v[156:157], v[158:159], v[156:157]
	v_lshl_add_u64 v[154:155], v[154:155], 0, v[142:143]
	v_cvt_pk_bf16_f32 v153, v156, v157
	global_store_dwordx4 v[154:155], v[150:153], off nt
	v_pk_mul_f32 v[154:155], v[6:7], v[38:39]
	v_pk_mul_f32 v[156:157], v[4:5], v[36:37]
	v_pk_mul_f32 v[150:151], v[36:37], s[20:21] op_sel_hi:[1,0]
	v_pk_mul_f32 v[152:153], v[38:39], s[20:21] op_sel_hi:[1,0]
	v_exp_f32_e32 v150, v150
	v_exp_f32_e32 v151, v151
	v_exp_f32_e32 v152, v152
	v_exp_f32_e32 v153, v153
	v_pk_mul_f32 v[158:159], v[2:3], v[34:35]
	v_pk_add_f32 v[150:151], v[150:151], 1.0 op_sel_hi:[1,0]
	v_pk_mul_f32 v[160:161], v[0:1], v[32:33]
	v_pk_add_f32 v[152:153], v[152:153], 1.0 op_sel_hi:[1,0]
	v_rcp_f32_e32 v150, v150
	v_rcp_f32_e32 v151, v151
	v_rcp_f32_e32 v152, v152
	v_rcp_f32_e32 v153, v153
	v_add_u32_e32 v149, 0xb0, v149
	v_pk_mul_f32 v[150:151], v[156:157], v[150:151]
	v_pk_mul_f32 v[156:157], v[34:35], s[20:21] op_sel_hi:[1,0]
	v_pk_mul_f32 v[152:153], v[154:155], v[152:153]
	v_pk_mul_f32 v[154:155], v[32:33], s[20:21] op_sel_hi:[1,0]
	v_exp_f32_e32 v156, v156
	v_exp_f32_e32 v154, v154
	v_exp_f32_e32 v155, v155
	v_exp_f32_e32 v157, v157
	v_mad_i64_i32 v[140:141], s[30:31], v149, s61, v[140:141]
	v_pk_add_f32 v[154:155], v[154:155], 1.0 op_sel_hi:[1,0]
	v_pk_add_f32 v[156:157], v[156:157], 1.0 op_sel_hi:[1,0]
	v_rcp_f32_e32 v154, v154
	v_rcp_f32_e32 v155, v155
	v_rcp_f32_e32 v156, v156
	v_rcp_f32_e32 v157, v157
	v_cvt_pk_bf16_f32 v150, v150, v151
	v_pk_mul_f32 v[154:155], v[160:161], v[154:155]
	v_cvt_pk_bf16_f32 v151, v152, v153
	v_pk_mul_f32 v[156:157], v[158:159], v[156:157]
	v_cvt_pk_bf16_f32 v152, v154, v155
	v_cvt_pk_bf16_f32 v153, v156, v157
	v_lshl_add_u64 v[140:141], v[140:141], 0, v[142:143]
	global_store_dwordx4 v[140:141], v[150:153], off nt
	s_cbranch_vccnz .LBB0_1236
	s_andn2_b64 vcc, exec, s[14:15]
	s_cbranch_vccnz .LBB0_1235
	s_barrier
	s_branch .LBB0_1235
